# GEMM2 epilogue: the tile's gate vector staged to LDS by one LDS-DMA load in the last K iteration and read with ds_read_b128, so the first row group starts without a global-load wait
# baseline (speedup 1.0000x reference)
.LBB0_791:
	global_load_dwordx4 v[6:9], v[110:111], off
	global_load_dwordx4 v[2:5], v[110:111], off offset:256
	s_sub_i32 s98, s0, 64
	s_lshr_b32 s98, s98, 6
	s_lshr_b32 s99, s0, 3
	s_add_i32 s98, s98, 8
	s_cmp_lt_i32 s0, 64
	s_cselect_b32 s98, s99, s98
	s_mulk_i32 s98, 0xc00
	v_lshlrev_b32_e32 v112, 4, v233
	s_add_i32 s98, s98, s46
	s_ashr_i32 s99, s98, 31
	s_lshl_b64 s[98:99], s[98:99], 2
	s_add_u32 s98, s80, s98
	s_addc_u32 s99, s81, s99
	s_add_i32 m0, s25, 0x20000
	s_nop 0
	global_load_lds_dwordx4 v112, s[98:99]

.LBB0_795:
	s_sub_i32 s10, s0, 64
	s_lshr_b32 s10, s10, 6
	s_lshr_b32 s1, s0, 3
	s_add_i32 s10, s10, 8
	s_cmp_lt_i32 s0, 64
	s_cselect_b32 s0, s1, s10
	v_or_b32_e32 v228, 16, v210
	v_or_b32_e32 v222, s46, v241
	s_mulk_i32 s0, 0xc00
	v_ashrrev_i32_e32 v229, 31, v228
	s_ashr_i32 s1, s0, 31
	v_ashrrev_i32_e32 v223, 31, v222
	v_lshlrev_b64 v[154:155], 11, v[228:229]
	v_or_b32_e32 v224, 32, v210
	s_lshl_b64 s[0:1], s[0:1], 2
	v_lshl_add_u64 v[154:155], s[60:61], 0, v[154:155]
	v_lshlrev_b64 v[246:247], 1, v[222:223]
	v_ashrrev_i32_e32 v225, 31, v224
	s_add_u32 s0, s80, s0
	v_lshl_add_u64 v[230:231], v[154:155], 0, v[246:247]
	v_lshlrev_b64 v[154:155], 11, v[224:225]
	v_or_b32_e32 v218, 48, v210
	s_addc_u32 s1, s81, s1
	v_lshl_add_u64 v[154:155], s[60:61], 0, v[154:155]
	v_ashrrev_i32_e32 v219, 31, v218
	s_nop 0
	v_lshl_add_u64 v[226:227], v[154:155], 0, v[246:247]
	v_lshlrev_b64 v[154:155], 11, v[218:219]
	s_add_i32 s98, s25, 0x20000
	v_lshl_add_u32 v118, v241, 2, s98
	s_nop 0
	ds_read_b128 v[122:125], v118 offset:16
	ds_read_b128 v[126:129], v118
	ds_read_b128 v[110:113], v118 offset:528
	ds_read_b128 v[118:121], v118 offset:512
	v_lshl_add_u64 v[154:155], s[60:61], 0, v[154:155]
	v_lshl_add_u64 v[220:221], v[154:155], 0, v[246:247]
	global_load_dwordx4 v[182:185], v[230:231], off
	global_load_dwordx4 v[178:181], v[230:231], off offset:256
	global_load_dwordx4 v[174:177], v[226:227], off
	global_load_dwordx4 v[170:173], v[226:227], off offset:256
	global_load_dwordx4 v[166:169], v[220:221], off
	global_load_dwordx4 v[162:165], v[220:221], off offset:256
	v_and_b32_e32 v155, 64, v237
	v_xor_b32_e32 v154, 16, v237
	v_add_u32_e32 v155, 64, v155
	v_cmp_lt_i32_e32 vcc, v154, v155
	v_add_u32_e32 v214, 0x80, v210
	s_nop 0
	v_cndmask_b32_e32 v154, v237, v154, vcc
	v_lshlrev_b32_e32 v244, 2, v154
	v_xor_b32_e32 v154, 32, v237
	v_cmp_lt_i32_e32 vcc, v154, v155
	s_nop 1
	v_cndmask_b32_e32 v154, v237, v154, vcc
	v_lshlrev_b32_e32 v243, 2, v154
	v_ashrrev_i32_e32 v215, 31, v214
	v_lshlrev_b64 v[154:155], 11, v[214:215]
	v_lshl_add_u64 v[154:155], s[60:61], 0, v[154:155]
	v_lshl_add_u64 v[216:217], v[154:155], 0, v[246:247]
	global_load_dwordx4 v[158:161], v[216:217], off
	global_load_dwordx4 v[154:157], v[216:217], off offset:256
	v_lshl_add_u64 v[212:213], v[212:213], 0, v[246:247]
	s_waitcnt vmcnt(16) lgkmcnt(0)
	v_cvt_f32_f16_sdwa v247, v6 dst_sel:DWORD dst_unused:UNUSED_PAD src0_sel:WORD_1
	v_cvt_f32_f16_e32 v246, v6
	v_cvt_f32_f16_sdwa v251, v7 dst_sel:DWORD dst_unused:UNUSED_PAD src0_sel:WORD_1
	v_cvt_f32_f16_e32 v250, v7
	v_cvt_f32_f16_sdwa v249, v8 dst_sel:DWORD dst_unused:UNUSED_PAD src0_sel:WORD_1
	v_cvt_f32_f16_sdwa v253, v9 dst_sel:DWORD dst_unused:UNUSED_PAD src0_sel:WORD_1
	v_cvt_f32_f16_e32 v252, v9
	v_cvt_f32_f16_e32 v248, v8
	v_pk_fma_f32 v[152:153], v[152:153], v[128:129], v[250:251]
	v_pk_fma_f32 v[150:151], v[150:151], v[126:127], v[246:247]
	v_pk_fma_f32 v[246:247], v[148:149], v[124:125], v[252:253]
	v_pk_fma_f32 v[148:149], v[146:147], v[122:123], v[248:249]
	v_mul_f32_e32 v146, v151, v151
	v_mul_f32_e32 v147, v153, v153
	v_fmac_f32_e32 v146, v150, v150
	v_fmac_f32_e32 v147, v152, v152
	v_add_f32_e32 v146, v146, v147
	v_mul_f32_e32 v147, v149, v149
	v_fmac_f32_e32 v147, v148, v148
	v_add_f32_e32 v146, v146, v147
	v_mul_f32_e32 v147, v247, v247
	v_fmac_f32_e32 v147, v246, v246
	v_add_f32_e32 v245, v147, v146
	v_cvt_pk_f16_f32 v146, v150, v151
	v_cvt_f32_f16_sdwa v151, v2 dst_sel:DWORD dst_unused:UNUSED_PAD src0_sel:WORD_1
	v_cvt_f32_f16_e32 v150, v2
	v_cvt_f32_f16_sdwa v249, v3 dst_sel:DWORD dst_unused:UNUSED_PAD src0_sel:WORD_1
	v_cvt_f32_f16_e32 v248, v3
	v_cvt_pk_f16_f32 v147, v152, v153
	v_cvt_f32_f16_sdwa v153, v4 dst_sel:DWORD dst_unused:UNUSED_PAD src0_sel:WORD_1
	v_cvt_f32_f16_e32 v152, v4
	v_cvt_f32_f16_sdwa v251, v5 dst_sel:DWORD dst_unused:UNUSED_PAD src0_sel:WORD_1
	v_cvt_f32_f16_e32 v250, v5
	v_pk_fma_f32 v[144:145], v[144:145], v[120:121], v[248:249]
	v_pk_fma_f32 v[142:143], v[142:143], v[118:119], v[150:151]
	v_pk_fma_f32 v[152:153], v[138:139], v[110:111], v[152:153]
	v_mul_f32_e32 v138, v143, v143
	v_mul_f32_e32 v139, v145, v145
	v_fmac_f32_e32 v138, v142, v142
	v_fmac_f32_e32 v139, v144, v144
	v_add_f32_e32 v138, v138, v139
	v_mul_f32_e32 v139, v153, v153
	v_pk_fma_f32 v[150:151], v[140:141], v[112:113], v[250:251]
	v_fmac_f32_e32 v139, v152, v152
	v_add_f32_e32 v138, v138, v139
	v_mul_f32_e32 v139, v151, v151
	v_fmac_f32_e32 v139, v150, v150
	v_add_f32_e32 v138, v139, v138
	v_add_f32_e32 v138, v245, v138
	ds_bpermute_b32 v139, v244, v138
	v_cvt_pk_f16_f32 v148, v148, v149
	v_cvt_pk_f16_f32 v149, v246, v247
	v_cvt_pk_f16_f32 v140, v142, v143
	v_cvt_pk_f16_f32 v141, v144, v145
	s_waitcnt lgkmcnt(0)
	v_add_f32_e32 v138, v138, v139
	ds_bpermute_b32 v139, v243, v138
	v_cvt_pk_f16_f32 v142, v152, v153
	v_cvt_pk_f16_f32 v143, v150, v151
	global_store_dwordx4 v[212:213], v[146:149], off
	global_store_dwordx4 v[212:213], v[140:143], off offset:256
	s_and_saveexec_b64 s[46:47], s[38:39]
	s_cbranch_execz .LBB0_797
	v_lshl_add_u64 v[140:141], v[210:211], 2, s[86:87]
	s_waitcnt lgkmcnt(0)
	v_add_f32_e32 v138, v138, v139
	global_atomic_add_f32 v[140:141], v138, off
